# E52: mixer work queues (both layers): the s_waitcnt vmcnt(0) store-drain before the dequeue barrier removed, so the previous unit's output stores drain under the dequeue atomic; on E41
# baseline (speedup 1.0000x reference)
.LBB0_316:
	s_barrier
	s_and_saveexec_b64 s[4:5], s[0:1]
	s_cbranch_execz .LBB0_320
	s_mov_b64 s[40:41], exec
	v_mbcnt_lo_u32_b32 v4, s40, 0
	v_mbcnt_hi_u32_b32 v4, s41, v4
	v_cmp_eq_u32_e32 vcc, 0, v4
	s_and_saveexec_b64 s[6:7], vcc
	s_cbranch_execz .LBB0_319
	s_bcnt1_i32_b64 s18, s[40:41]
	v_mov_b32_e32 v6, s18
	global_atomic_add v6, v5, v6, s[82:83] offset:256 sc0

.LBB0_1229:
	s_barrier
	s_and_saveexec_b64 s[18:19], s[4:5]
	s_cbranch_execz .LBB0_1233
	s_mov_b64 s[22:23], exec
	s_waitcnt lgkmcnt(0)
	v_mbcnt_lo_u32_b32 v2, s22, 0
	v_mbcnt_hi_u32_b32 v2, s23, v2
	v_cmp_eq_u32_e32 vcc, 0, v2
	s_and_saveexec_b64 s[20:21], vcc
	s_cbranch_execz .LBB0_1232
	s_bcnt1_i32_b64 s3, s[22:23]
	v_mov_b32_e32 v4, s3
	global_atomic_add v4, v3, v4, s[82:83] offset:512 sc0
